# on top of v10: the one-time same-XCD membership check fetches its 32 words together instead of 32 serialized round trips
# speedup vs baseline: 1.0033x; 1.0033x over previous
; __device__ __forceinline__ unsigned xb_ld(unsigned* p)              { return __hip_atomic_load(p, __ATOMIC_RELAXED, __HIP_MEMORY_SCOPE_AGENT); }
; __device__ __forceinline__ unsigned xb_xcc_id() { return (unsigned)__builtin_amdgcn_s_getreg((3 << 11) | 20) & 0xFu; }
; #define XB_THREAD0(w) ((w) == 0 && lane_opaque() == 0)
; __device__ __forceinline__ Frame phase_frame(const Frame& F) { Frame P = F; asm volatile("" : "+s"(P.wave), "+s"(P.gw), "+s"(P.ws), "+s"(P.out)); return P; }
; #define SEAM(k) do { if (IN(k) && IN((k) + 1)) { if (glocal && (k) != 0 && (k) != NPHASE - 2) grp_barrier(ctlw, barw, gx, gn, F.wave, MISC + 12); else xcd_barrier(bar); } } while (0)
; __global__ void __launch_bounds__(NTHR, 2) trunk_fwd(Args args) {
;     ...
;     if (glocal && XB_THREAD0(F.wave)) __hip_atomic_store(&ctlw[GB_XCC(blockIdx.x)], xb_xcc_id() + 1u, RLX_AGENT);
;     ...
;     if (IN(0)) { const Frame P = phase_frame(F); for (int rep = 0; rep < ((PROBE_DUP >> 6) & 1) + 1; ++rep) p0_prologue(P, args); }
;     SEAM(0);
;     if (glocal && IN(0) && IN(1)) {
;         if (XB_THREAD0(F.wave)) { const unsigned me = xb_xcc_id() + 1u; unsigned ok = 1u;
;             for (unsigned j = 0; j < gn; ++j) ok &= (xb_ld(&ctlw[GB_XCC(j * 8u + gx)]) == me) ? 1u : 0u;
;             MISC[12] = ok; }
;         __syncthreads(); }
.LBB0_141:
	v_writelane_b32 v253, s84, 48
	s_and_b32 s4, s2, 7
	s_xor_b32 s2, s4, 7
	v_writelane_b32 v253, s85, 49
	v_writelane_b32 v253, s82, 50
	s_add_i32 s5, s2, s86
	s_nop 0
	v_writelane_b32 v253, s83, 51
	s_nop 0
	v_readlane_b32 s2, v253, 24
	v_readlane_b32 s3, v253, 25
	s_and_b64 s[2:3], s[8:9], s[2:3]
	s_and_b64 s[0:1], s[0:1], s[2:3]
	s_andn2_b64 vcc, exec, s[0:1]
	s_lshr_b32 s0, s5, 3
	v_writelane_b32 v253, s0, 52
	s_cbranch_vccnz .LBB0_149
	v_readlane_b32 s0, v253, 46
	v_readlane_b32 s1, v253, 47
	s_and_b64 vcc, exec, s[0:1]
	s_cbranch_vccnz .LBB0_148
	v_mbcnt_lo_u32_b32 v0, -1, 0
	v_mbcnt_hi_u32_b32 v0, -1, v0
	s_nop 0
	v_cmp_eq_u32_e32 vcc, 0, v0
	s_and_saveexec_b64 s[0:1], vcc
	s_cbranch_execz .LBB0_147
	s_getreg_b32 s2, hwreg(HW_REG_XCC_ID, 0, 4)
	s_and_b32 s5, s2, 15
	s_add_i32 s5, s5, 1
	s_lshl_b32 s2, s4, 2
	s_add_u32 s2, s90, s2
	s_addc_u32 s3, s91, 0
	s_add_u32 s2, s2, 0x3000
	s_addc_u32 s3, s3, 0
	v_mov_b32_e32 v0, 1
	v_mov_b32_e32 v1, 0
	v_readlane_b32 s8, v253, 52
	global_load_dword v2, v1, s[2:3] sc1
	global_load_dword v3, v1, s[2:3] offset:32 sc1
	global_load_dword v4, v1, s[2:3] offset:64 sc1
	global_load_dword v5, v1, s[2:3] offset:96 sc1
	global_load_dword v6, v1, s[2:3] offset:128 sc1
	global_load_dword v7, v1, s[2:3] offset:160 sc1
	global_load_dword v8, v1, s[2:3] offset:192 sc1
	global_load_dword v9, v1, s[2:3] offset:224 sc1
	global_load_dword v10, v1, s[2:3] offset:256 sc1
	global_load_dword v11, v1, s[2:3] offset:288 sc1
	global_load_dword v12, v1, s[2:3] offset:320 sc1
	global_load_dword v13, v1, s[2:3] offset:352 sc1
	global_load_dword v14, v1, s[2:3] offset:384 sc1
	global_load_dword v15, v1, s[2:3] offset:416 sc1
	global_load_dword v16, v1, s[2:3] offset:448 sc1
	global_load_dword v17, v1, s[2:3] offset:480 sc1
	global_load_dword v18, v1, s[2:3] offset:512 sc1
	global_load_dword v19, v1, s[2:3] offset:544 sc1
	global_load_dword v20, v1, s[2:3] offset:576 sc1
	global_load_dword v21, v1, s[2:3] offset:608 sc1
	global_load_dword v22, v1, s[2:3] offset:640 sc1
	global_load_dword v23, v1, s[2:3] offset:672 sc1
	global_load_dword v24, v1, s[2:3] offset:704 sc1
	global_load_dword v25, v1, s[2:3] offset:736 sc1
	global_load_dword v26, v1, s[2:3] offset:768 sc1
	global_load_dword v27, v1, s[2:3] offset:800 sc1
	global_load_dword v28, v1, s[2:3] offset:832 sc1
	global_load_dword v29, v1, s[2:3] offset:864 sc1
	global_load_dword v30, v1, s[2:3] offset:896 sc1
	global_load_dword v31, v1, s[2:3] offset:928 sc1
	global_load_dword v32, v1, s[2:3] offset:960 sc1
	global_load_dword v33, v1, s[2:3] offset:992 sc1
	s_waitcnt vmcnt(0)
	v_xor_b32_e32 v34, s5, v2
	v_xor_b32_e32 v35, s5, v3
	v_or_b32_e32 v34, v34, v35
	v_xor_b32_e32 v35, s5, v4
	v_or_b32_e32 v34, v34, v35
	v_xor_b32_e32 v35, s5, v5
	v_or_b32_e32 v34, v34, v35
	v_xor_b32_e32 v35, s5, v6
	v_or_b32_e32 v34, v34, v35
	v_xor_b32_e32 v35, s5, v7
	v_or_b32_e32 v34, v34, v35
	v_xor_b32_e32 v35, s5, v8
	v_or_b32_e32 v34, v34, v35
	v_xor_b32_e32 v35, s5, v9
	v_or_b32_e32 v34, v34, v35
	v_xor_b32_e32 v35, s5, v10
	v_or_b32_e32 v34, v34, v35
	v_xor_b32_e32 v35, s5, v11
	v_or_b32_e32 v34, v34, v35
	v_xor_b32_e32 v35, s5, v12
	v_or_b32_e32 v34, v34, v35
	v_xor_b32_e32 v35, s5, v13
	v_or_b32_e32 v34, v34, v35
	v_xor_b32_e32 v35, s5, v14
	v_or_b32_e32 v34, v34, v35
	v_xor_b32_e32 v35, s5, v15
	v_or_b32_e32 v34, v34, v35
	v_xor_b32_e32 v35, s5, v16
	v_or_b32_e32 v34, v34, v35
	v_xor_b32_e32 v35, s5, v17
	v_or_b32_e32 v34, v34, v35
	v_xor_b32_e32 v35, s5, v18
	v_or_b32_e32 v34, v34, v35
	v_xor_b32_e32 v35, s5, v19
	v_or_b32_e32 v34, v34, v35
	v_xor_b32_e32 v35, s5, v20
	v_or_b32_e32 v34, v34, v35
	v_xor_b32_e32 v35, s5, v21
	v_or_b32_e32 v34, v34, v35
	v_xor_b32_e32 v35, s5, v22
	v_or_b32_e32 v34, v34, v35
	v_xor_b32_e32 v35, s5, v23
	v_or_b32_e32 v34, v34, v35
	v_xor_b32_e32 v35, s5, v24
	v_or_b32_e32 v34, v34, v35
	v_xor_b32_e32 v35, s5, v25
	v_or_b32_e32 v34, v34, v35
	v_xor_b32_e32 v35, s5, v26
	v_or_b32_e32 v34, v34, v35
	v_xor_b32_e32 v35, s5, v27
	v_or_b32_e32 v34, v34, v35
	v_xor_b32_e32 v35, s5, v28
	v_or_b32_e32 v34, v34, v35
	v_xor_b32_e32 v35, s5, v29
	v_or_b32_e32 v34, v34, v35
	v_xor_b32_e32 v35, s5, v30
	v_or_b32_e32 v34, v34, v35
	v_xor_b32_e32 v35, s5, v31
	v_or_b32_e32 v34, v34, v35
	v_xor_b32_e32 v35, s5, v32
	v_or_b32_e32 v34, v34, v35
	v_xor_b32_e32 v35, s5, v33
	v_or_b32_e32 v34, v34, v35
	v_cmp_eq_u32_e32 vcc, 0, v34
	s_nop 1
	v_cndmask_b32_e32 v0, 0, v0, vcc
	s_add_i32 s2, 0, 0x20970
	v_mov_b32_e32 v1, s2
	ds_write_b32 v1, v0
